# SSD unit: the output wave's elementwise prep split across partner waves (wave 1: silu(z), wave 2: decay factors) and handed over through LDS
# baseline (speedup 1.0000x reference)
.Lssd0_loop:
.Lssd0_blk0:
	s_nop 15
	s_add_i32 s0, s81, -1
	s_add_i32 s83, s80, 1
	s_min_i32 s83, s83, s0
	s_add_i32 s93, s80, 2
	s_min_i32 s93, s93, s0
	s_add_i32 s95, s80, 3
	s_min_i32 s95, s95, s0
	s_lshl_b32 s0, s93, 9
	s_add_u32 s76, s62, s0
	s_addc_u32 s77, s63, 0
	s_mul_i32 s0, s80, 0x2a000
	s_add_u32 s66, s28, s0
	s_addc_u32 s67, s29, 0
	s_mul_i32 s0, s83, 0x2a000
	s_add_u32 s68, s28, s0
	s_addc_u32 s69, s29, 0
	s_add_u32 s72, s30, s0
	s_addc_u32 s73, s31, 0
	s_mul_i32 s0, s93, 0x2a000
	s_add_u32 s70, s28, s0
	s_addc_u32 s71, s29, 0
	s_add_u32 s74, s30, s0
	s_addc_u32 s75, s31, 0
	s_mul_i32 s0, s95, 0x2a000
	s_add_u32 s78, s64, s0
	s_addc_u32 s79, s65, 0
	s_waitcnt vmcnt(37)
	v_add_f32_e32 v40, s12, v60
	v_mul_f32_e32 v41, 0x3fb8aa3b, v40
	v_exp_f32_e32 v41, v41
	s_nop 0
	v_add_f32_e32 v41, 1.0, v41
	v_log_f32_e32 v41, v41
	s_nop 0
	v_mul_f32_e32 v41, 0x3f317218, v41
	v_cmp_lt_f32_e32 vcc, 0x41a00000, v40
	s_nop 1
	v_cndmask_b32_e32 v122, v41, v40, vcc
	v_mul_f32_e32 v40, s25, v122
	s_nop 1
	v_add_f32_dpp v41, v40, v40 row_shr:1 row_mask:0xf bank_mask:0xf bound_ctrl:1
	s_nop 1
	v_add_f32_dpp v40, v41, v41 row_shr:2 row_mask:0xf bank_mask:0xf bound_ctrl:1
	s_nop 1
	v_add_f32_dpp v41, v40, v40 row_shr:4 row_mask:0xf bank_mask:0xf bound_ctrl:1
	s_nop 1
	v_add_f32_dpp v121, v41, v41 row_shr:8 row_mask:0xf bank_mask:0xf bound_ctrl:1
	s_nop 0
	v_readlane_b32 s32, v121, 15
	ds_bpermute_b32 v96, v88, v121
	ds_bpermute_b32 v97, v89, v121
	ds_bpermute_b32 v98, v90, v121
	ds_bpermute_b32 v99, v91, v121
	ds_bpermute_b32 v104, v88, v122
	ds_bpermute_b32 v105, v89, v122
	ds_bpermute_b32 v106, v90, v122
	ds_bpermute_b32 v107, v91, v122
	v_exp_f32_e32 v120, s32
	s_waitcnt lgkmcnt(0)
	v_sub_f32_e32 v108, s32, v96
	v_mul_f32_e32 v104, v48, v104
	v_sub_f32_e32 v109, s32, v97
	v_mul_f32_e32 v105, v49, v105
	v_sub_f32_e32 v110, s32, v98
	v_mul_f32_e32 v106, v50, v106
	v_sub_f32_e32 v111, s32, v99
	v_mul_f32_e32 v107, v51, v107
	v_exp_f32_e32 v108, v108
	v_exp_f32_e32 v109, v109
	v_exp_f32_e32 v110, v110
	v_exp_f32_e32 v111, v111
	v_mul_f32_e32 v108, v104, v108
	v_mul_f32_e32 v109, v105, v109
	v_mul_f32_e32 v110, v106, v110
	v_mul_f32_e32 v111, v107, v111
	s_waitcnt vmcnt(56)
	v_mfma_f32_16x16x4_f32 v[36:39], v4, v20, 0
	v_mfma_f32_16x16x4_f32 v[44:47], v20, v72, 0
	global_load_short_d16_hi v20, v80, s[74:75] offset:512
	global_load_short_d16_hi v4, v80, s[74:75] offset:0
	s_waitcnt vmcnt(56)
	v_mfma_f32_16x16x4_f32 v[36:39], v5, v21, v[36:39]
	v_mfma_f32_16x16x4_f32 v[44:47], v21, v73, v[44:47]
	global_load_short_d16_hi v21, v80, s[74:75] offset:514
	global_load_short_d16_hi v5, v80, s[74:75] offset:2
	s_waitcnt vmcnt(56)
	v_mfma_f32_16x16x4_f32 v[36:39], v6, v22, v[36:39]
	v_mfma_f32_16x16x4_f32 v[44:47], v22, v74, v[44:47]
	global_load_short_d16_hi v22, v80, s[74:75] offset:516
	global_load_short_d16_hi v6, v80, s[74:75] offset:4
	s_waitcnt vmcnt(56)
	v_mfma_f32_16x16x4_f32 v[36:39], v7, v23, v[36:39]
	v_mfma_f32_16x16x4_f32 v[44:47], v23, v75, v[44:47]
	global_load_short_d16_hi v23, v80, s[74:75] offset:518
	global_load_short_d16_hi v7, v80, s[74:75] offset:6
	s_waitcnt vmcnt(56)
	v_mfma_f32_16x16x4_f32 v[36:39], v8, v24, v[36:39]
	v_mfma_f32_16x16x4_f32 v[44:47], v24, v76, v[44:47]
	global_load_short_d16_hi v24, v80, s[74:75] offset:544
	global_load_short_d16_hi v8, v80, s[74:75] offset:32
	s_waitcnt vmcnt(56)
	v_mfma_f32_16x16x4_f32 v[36:39], v9, v25, v[36:39]
	v_mfma_f32_16x16x4_f32 v[44:47], v25, v77, v[44:47]
	global_load_short_d16_hi v25, v80, s[74:75] offset:546
	global_load_short_d16_hi v9, v80, s[74:75] offset:34
	s_waitcnt vmcnt(56)
	v_mfma_f32_16x16x4_f32 v[36:39], v10, v26, v[36:39]
	v_mfma_f32_16x16x4_f32 v[44:47], v26, v78, v[44:47]
	global_load_short_d16_hi v26, v80, s[74:75] offset:548
	global_load_short_d16_hi v10, v80, s[74:75] offset:36
	s_waitcnt vmcnt(56)
	v_mfma_f32_16x16x4_f32 v[36:39], v11, v27, v[36:39]
	v_mfma_f32_16x16x4_f32 v[44:47], v27, v79, v[44:47]
	global_load_short_d16_hi v27, v80, s[74:75] offset:550
	global_load_short_d16_hi v11, v80, s[74:75] offset:38
	s_cmp_eq_u32 s82, 0
	s_cbranch_scc1 .Lssd0_w0_0
	s_nop 5
	ds_write_b128 v123, v[36:39] offset:0
	ds_write_b128 v123, v[44:47] offset:4096
	s_cmp_eq_u32 s82, 1
	s_cbranch_scc0 .Lssd0_nw1_0
	s_waitcnt vmcnt(29)
	v_mul_f32_e32 v116, 0xbfb8aa3b, v56
	v_mul_f32_e32 v117, 0xbfb8aa3b, v57
	v_mul_f32_e32 v118, 0xbfb8aa3b, v58
	v_mul_f32_e32 v119, 0xbfb8aa3b, v59
	v_exp_f32_e32 v116, v116
	v_exp_f32_e32 v117, v117
	v_exp_f32_e32 v118, v118
	v_exp_f32_e32 v119, v119
	v_add_f32_e32 v116, 1.0, v116
	v_add_f32_e32 v117, 1.0, v117
	v_add_f32_e32 v118, 1.0, v118
	v_add_f32_e32 v119, 1.0, v119
	v_rcp_f32_e32 v116, v116
	v_rcp_f32_e32 v117, v117
	v_rcp_f32_e32 v118, v118
	v_rcp_f32_e32 v119, v119
	v_mul_f32_e32 v116, v116, v56
	v_mul_f32_e32 v117, v117, v57
	v_mul_f32_e32 v118, v118, v58
	v_mul_f32_e32 v119, v119, v59
	ds_write_b128 v124, v[116:119] offset:16384
	global_load_short_d16_hi v56, v81, s[68:69]
	global_load_short_d16_hi v57, v82, s[68:69]
	global_load_short_d16_hi v58, v83, s[68:69]
	global_load_short_d16_hi v59, v84, s[68:69]
	s_branch .Lssd0_pub_0
.Lssd0_nw1_0:
	s_cmp_eq_u32 s82, 2
	s_cbranch_scc0 .Lssd0_pub_0
	v_sub_f32_e32 v100, v121, v96
	v_sub_f32_e32 v101, v121, v97
	v_sub_f32_e32 v102, v121, v98
	v_sub_f32_e32 v103, v121, v99
	v_min_f32_e32 v100, 0, v100
	v_min_f32_e32 v101, 0, v101
	v_min_f32_e32 v102, 0, v102
	v_min_f32_e32 v103, 0, v103
	v_add_f32_e32 v100, v92, v100
	v_add_f32_e32 v101, v93, v101
	v_add_f32_e32 v102, v94, v102
	v_add_f32_e32 v103, v95, v103
	v_exp_f32_e32 v100, v100
	v_exp_f32_e32 v101, v101
	v_exp_f32_e32 v102, v102
	v_exp_f32_e32 v103, v103
	v_exp_f32_e32 v96, v96
	v_exp_f32_e32 v97, v97
	v_exp_f32_e32 v98, v98
	v_exp_f32_e32 v99, v99
	ds_write_b128 v124, v[100:103] offset:17408
	ds_write_b128 v124, v[96:99] offset:18432
.Lssd0_pub_0:
	s_waitcnt lgkmcnt(0)
	s_barrier
	s_branch .Lssd0_mrg_0
.Lssd0_w0_0:
	s_barrier
	ds_read_b128 v[128:131], v124 offset:1024
	ds_read_b128 v[132:135], v124 offset:5120
	ds_read_b128 v[136:139], v124 offset:2048
	ds_read_b128 v[140:143], v124 offset:6144
	ds_read_b128 v[144:147], v124 offset:3072
	ds_read_b128 v[150:153], v124 offset:7168
	ds_read_b128 v[116:119], v124 offset:16384
	ds_read_b128 v[100:103], v124 offset:17408
	ds_read_b128 v[96:99], v124 offset:18432
	v_mul_f32_e32 v112, s27, v48
	v_mul_f32_e32 v113, s27, v49
	v_mul_f32_e32 v114, s27, v50
	v_mul_f32_e32 v115, s27, v51
	s_waitcnt lgkmcnt(0)
	v_add_f32_e32 v36, v36, v128
	v_add_f32_e32 v37, v37, v129
	v_add_f32_e32 v38, v38, v130
	v_add_f32_e32 v39, v39, v131
	v_add_f32_e32 v44, v44, v132
	v_add_f32_e32 v45, v45, v133
	v_add_f32_e32 v46, v46, v134
	v_add_f32_e32 v47, v47, v135
	v_add_f32_e32 v36, v36, v136
	v_add_f32_e32 v37, v37, v137
	v_add_f32_e32 v38, v38, v138
	v_add_f32_e32 v39, v39, v139
	v_add_f32_e32 v44, v44, v140
	v_add_f32_e32 v45, v45, v141
	v_add_f32_e32 v46, v46, v142
	v_add_f32_e32 v47, v47, v143
	v_add_f32_e32 v36, v36, v144
	v_add_f32_e32 v37, v37, v145
	v_add_f32_e32 v38, v38, v146
	v_add_f32_e32 v39, v39, v147
	v_add_f32_e32 v44, v44, v150
	v_add_f32_e32 v45, v45, v151
	v_add_f32_e32 v46, v46, v152
	v_add_f32_e32 v47, v47, v153
	v_mul_f32_e32 v36, v36, v100
	v_mul_f32_e32 v37, v37, v101
	v_mul_f32_e32 v38, v38, v102
	v_mul_f32_e32 v39, v39, v103
	v_mul_f32_e32 v44, v44, v96
	v_mul_f32_e32 v45, v45, v97
	v_mul_f32_e32 v46, v46, v98
	v_mul_f32_e32 v47, v47, v99
	s_nop 0
	s_nop 0
	v_mfma_f32_16x16x4_f32 v[44:47], v36, v104, v[44:47]
	v_mfma_f32_16x16x4_f32 v[44:47], v37, v105, v[44:47]
	v_mfma_f32_16x16x4_f32 v[44:47], v38, v106, v[44:47]
	v_mfma_f32_16x16x4_f32 v[44:47], v39, v107, v[44:47]
	global_load_dword v56, v86, s[78:79]
	s_nop 9
	v_add_f32_e32 v44, v44, v112
	v_add_f32_e32 v45, v45, v113
	v_add_f32_e32 v46, v46, v114
	v_add_f32_e32 v47, v47, v115
	v_mul_f32_e32 v44, v44, v116
	v_mul_f32_e32 v45, v45, v117
	v_mul_f32_e32 v46, v46, v118
	v_mul_f32_e32 v47, v47, v119
	v_cvt_pk_bf16_f32 v40, v44, v45
	v_cvt_pk_bf16_f32 v41, v46, v47
	global_store_short v81, v40, s[66:67]
	global_store_short_d16_hi v82, v40, s[66:67]
	global_store_short v83, v41, s[66:67]
	global_store_short_d16_hi v84, v41, s[66:67]

.Lssd0_blk1:
	s_nop 15
	s_add_i32 s0, s81, -1
	s_add_i32 s83, s80, 1
	s_min_i32 s83, s83, s0
	s_add_i32 s93, s80, 2
	s_min_i32 s93, s93, s0
	s_add_i32 s95, s80, 3
	s_min_i32 s95, s95, s0
	s_lshl_b32 s0, s93, 9
	s_add_u32 s76, s62, s0
	s_addc_u32 s77, s63, 0
	s_mul_i32 s0, s80, 0x2a000
	s_add_u32 s66, s28, s0
	s_addc_u32 s67, s29, 0
	s_mul_i32 s0, s83, 0x2a000
	s_add_u32 s68, s28, s0
	s_addc_u32 s69, s29, 0
	s_add_u32 s72, s30, s0
	s_addc_u32 s73, s31, 0
	s_mul_i32 s0, s93, 0x2a000
	s_add_u32 s70, s28, s0
	s_addc_u32 s71, s29, 0
	s_add_u32 s74, s30, s0
	s_addc_u32 s75, s31, 0
	s_mul_i32 s0, s95, 0x2a000
	s_add_u32 s78, s64, s0
	s_addc_u32 s79, s65, 0
	s_waitcnt vmcnt(37)
	v_add_f32_e32 v40, s12, v61
	v_mul_f32_e32 v41, 0x3fb8aa3b, v40
	v_exp_f32_e32 v41, v41
	s_nop 0
	v_add_f32_e32 v41, 1.0, v41
	v_log_f32_e32 v41, v41
	s_nop 0
	v_mul_f32_e32 v41, 0x3f317218, v41
	v_cmp_lt_f32_e32 vcc, 0x41a00000, v40
	s_nop 1
	v_cndmask_b32_e32 v122, v41, v40, vcc
	v_mul_f32_e32 v40, s25, v122
	s_nop 1
	v_add_f32_dpp v41, v40, v40 row_shr:1 row_mask:0xf bank_mask:0xf bound_ctrl:1
	s_nop 1
	v_add_f32_dpp v40, v41, v41 row_shr:2 row_mask:0xf bank_mask:0xf bound_ctrl:1
	s_nop 1
	v_add_f32_dpp v41, v40, v40 row_shr:4 row_mask:0xf bank_mask:0xf bound_ctrl:1
	s_nop 1
	v_add_f32_dpp v121, v41, v41 row_shr:8 row_mask:0xf bank_mask:0xf bound_ctrl:1
	s_nop 0
	v_readlane_b32 s32, v121, 15
	ds_bpermute_b32 v96, v88, v121
	ds_bpermute_b32 v97, v89, v121
	ds_bpermute_b32 v98, v90, v121
	ds_bpermute_b32 v99, v91, v121
	ds_bpermute_b32 v104, v88, v122
	ds_bpermute_b32 v105, v89, v122
	ds_bpermute_b32 v106, v90, v122
	ds_bpermute_b32 v107, v91, v122
	v_exp_f32_e32 v120, s32
	s_waitcnt lgkmcnt(0)
	v_sub_f32_e32 v108, s32, v96
	v_mul_f32_e32 v104, v52, v104
	v_sub_f32_e32 v109, s32, v97
	v_mul_f32_e32 v105, v53, v105
	v_sub_f32_e32 v110, s32, v98
	v_mul_f32_e32 v106, v54, v106
	v_sub_f32_e32 v111, s32, v99
	v_mul_f32_e32 v107, v55, v107
	v_exp_f32_e32 v108, v108
	v_exp_f32_e32 v109, v109
	v_exp_f32_e32 v110, v110
	v_exp_f32_e32 v111, v111
	v_mul_f32_e32 v108, v104, v108
	v_mul_f32_e32 v109, v105, v109
	v_mul_f32_e32 v110, v106, v110
	v_mul_f32_e32 v111, v107, v111
	s_waitcnt vmcnt(56)
	v_mfma_f32_16x16x4_f32 v[36:39], v12, v28, 0
	v_mfma_f32_16x16x4_f32 v[44:47], v28, v72, 0
	global_load_short_d16_hi v28, v80, s[74:75] offset:512
	global_load_short_d16_hi v12, v80, s[74:75] offset:0
	s_waitcnt vmcnt(56)
	v_mfma_f32_16x16x4_f32 v[36:39], v13, v29, v[36:39]
	v_mfma_f32_16x16x4_f32 v[44:47], v29, v73, v[44:47]
	global_load_short_d16_hi v29, v80, s[74:75] offset:514
	global_load_short_d16_hi v13, v80, s[74:75] offset:2
	s_waitcnt vmcnt(56)
	v_mfma_f32_16x16x4_f32 v[36:39], v14, v30, v[36:39]
	v_mfma_f32_16x16x4_f32 v[44:47], v30, v74, v[44:47]
	global_load_short_d16_hi v30, v80, s[74:75] offset:516
	global_load_short_d16_hi v14, v80, s[74:75] offset:4
	s_waitcnt vmcnt(56)
	v_mfma_f32_16x16x4_f32 v[36:39], v15, v31, v[36:39]
	v_mfma_f32_16x16x4_f32 v[44:47], v31, v75, v[44:47]
	global_load_short_d16_hi v31, v80, s[74:75] offset:518
	global_load_short_d16_hi v15, v80, s[74:75] offset:6
	s_waitcnt vmcnt(56)
	v_mfma_f32_16x16x4_f32 v[36:39], v16, v32, v[36:39]
	v_mfma_f32_16x16x4_f32 v[44:47], v32, v76, v[44:47]
	global_load_short_d16_hi v32, v80, s[74:75] offset:544
	global_load_short_d16_hi v16, v80, s[74:75] offset:32
	s_waitcnt vmcnt(56)
	v_mfma_f32_16x16x4_f32 v[36:39], v17, v33, v[36:39]
	v_mfma_f32_16x16x4_f32 v[44:47], v33, v77, v[44:47]
	global_load_short_d16_hi v33, v80, s[74:75] offset:546
	global_load_short_d16_hi v17, v80, s[74:75] offset:34
	s_waitcnt vmcnt(56)
	v_mfma_f32_16x16x4_f32 v[36:39], v18, v34, v[36:39]
	v_mfma_f32_16x16x4_f32 v[44:47], v34, v78, v[44:47]
	global_load_short_d16_hi v34, v80, s[74:75] offset:548
	global_load_short_d16_hi v18, v80, s[74:75] offset:36
	s_waitcnt vmcnt(56)
	v_mfma_f32_16x16x4_f32 v[36:39], v19, v35, v[36:39]
	v_mfma_f32_16x16x4_f32 v[44:47], v35, v79, v[44:47]
	global_load_short_d16_hi v35, v80, s[74:75] offset:550
	global_load_short_d16_hi v19, v80, s[74:75] offset:38
	s_cmp_eq_u32 s82, 0
	s_cbranch_scc1 .Lssd0_w0_1
	s_nop 5
	ds_write_b128 v123, v[36:39] offset:8192
	ds_write_b128 v123, v[44:47] offset:12288
	s_cmp_eq_u32 s82, 1
	s_cbranch_scc0 .Lssd0_nw1_1
	s_waitcnt vmcnt(29)
	v_mul_f32_e32 v116, 0xbfb8aa3b, v56
	v_mul_f32_e32 v117, 0xbfb8aa3b, v57
	v_mul_f32_e32 v118, 0xbfb8aa3b, v58
	v_mul_f32_e32 v119, 0xbfb8aa3b, v59
	v_exp_f32_e32 v116, v116
	v_exp_f32_e32 v117, v117
	v_exp_f32_e32 v118, v118
	v_exp_f32_e32 v119, v119
	v_add_f32_e32 v116, 1.0, v116
	v_add_f32_e32 v117, 1.0, v117
	v_add_f32_e32 v118, 1.0, v118
	v_add_f32_e32 v119, 1.0, v119
	v_rcp_f32_e32 v116, v116
	v_rcp_f32_e32 v117, v117
	v_rcp_f32_e32 v118, v118
	v_rcp_f32_e32 v119, v119
	v_mul_f32_e32 v116, v116, v56
	v_mul_f32_e32 v117, v117, v57
	v_mul_f32_e32 v118, v118, v58
	v_mul_f32_e32 v119, v119, v59
	ds_write_b128 v124, v[116:119] offset:20480
	global_load_short_d16_hi v56, v81, s[68:69]
	global_load_short_d16_hi v57, v82, s[68:69]
	global_load_short_d16_hi v58, v83, s[68:69]
	global_load_short_d16_hi v59, v84, s[68:69]
	s_branch .Lssd0_pub_1
.Lssd0_nw1_1:
	s_cmp_eq_u32 s82, 2
	s_cbranch_scc0 .Lssd0_pub_1
	v_sub_f32_e32 v100, v121, v96
	v_sub_f32_e32 v101, v121, v97
	v_sub_f32_e32 v102, v121, v98
	v_sub_f32_e32 v103, v121, v99
	v_min_f32_e32 v100, 0, v100
	v_min_f32_e32 v101, 0, v101
	v_min_f32_e32 v102, 0, v102
	v_min_f32_e32 v103, 0, v103
	v_add_f32_e32 v100, v92, v100
	v_add_f32_e32 v101, v93, v101
	v_add_f32_e32 v102, v94, v102
	v_add_f32_e32 v103, v95, v103
	v_exp_f32_e32 v100, v100
	v_exp_f32_e32 v101, v101
	v_exp_f32_e32 v102, v102
	v_exp_f32_e32 v103, v103
	v_exp_f32_e32 v96, v96
	v_exp_f32_e32 v97, v97
	v_exp_f32_e32 v98, v98
	v_exp_f32_e32 v99, v99
	ds_write_b128 v124, v[100:103] offset:21504
	ds_write_b128 v124, v[96:99] offset:22528

.Lssd0_w0_1:
	s_barrier
	ds_read_b128 v[128:131], v124 offset:9216
	ds_read_b128 v[132:135], v124 offset:13312
	ds_read_b128 v[136:139], v124 offset:10240
	ds_read_b128 v[140:143], v124 offset:14336
	ds_read_b128 v[144:147], v124 offset:11264
	ds_read_b128 v[150:153], v124 offset:15360
	ds_read_b128 v[116:119], v124 offset:20480
	ds_read_b128 v[100:103], v124 offset:21504
	ds_read_b128 v[96:99], v124 offset:22528
	v_mul_f32_e32 v112, s27, v52
	v_mul_f32_e32 v113, s27, v53
	v_mul_f32_e32 v114, s27, v54
	v_mul_f32_e32 v115, s27, v55
	s_waitcnt lgkmcnt(0)
	v_add_f32_e32 v36, v36, v128
	v_add_f32_e32 v37, v37, v129
	v_add_f32_e32 v38, v38, v130
	v_add_f32_e32 v39, v39, v131
	v_add_f32_e32 v44, v44, v132
	v_add_f32_e32 v45, v45, v133
	v_add_f32_e32 v46, v46, v134
	v_add_f32_e32 v47, v47, v135
	v_add_f32_e32 v36, v36, v136
	v_add_f32_e32 v37, v37, v137
	v_add_f32_e32 v38, v38, v138
	v_add_f32_e32 v39, v39, v139
	v_add_f32_e32 v44, v44, v140
	v_add_f32_e32 v45, v45, v141
	v_add_f32_e32 v46, v46, v142
	v_add_f32_e32 v47, v47, v143
	v_add_f32_e32 v36, v36, v144
	v_add_f32_e32 v37, v37, v145
	v_add_f32_e32 v38, v38, v146
	v_add_f32_e32 v39, v39, v147
	v_add_f32_e32 v44, v44, v150
	v_add_f32_e32 v45, v45, v151
	v_add_f32_e32 v46, v46, v152
	v_add_f32_e32 v47, v47, v153
	v_mul_f32_e32 v36, v36, v100
	v_mul_f32_e32 v37, v37, v101
	v_mul_f32_e32 v38, v38, v102
	v_mul_f32_e32 v39, v39, v103
	v_mul_f32_e32 v44, v44, v96
	v_mul_f32_e32 v45, v45, v97
	v_mul_f32_e32 v46, v46, v98
	v_mul_f32_e32 v47, v47, v99
	s_nop 0
	s_nop 0
	v_mfma_f32_16x16x4_f32 v[44:47], v36, v104, v[44:47]
	v_mfma_f32_16x16x4_f32 v[44:47], v37, v105, v[44:47]
	v_mfma_f32_16x16x4_f32 v[44:47], v38, v106, v[44:47]
	v_mfma_f32_16x16x4_f32 v[44:47], v39, v107, v[44:47]
	global_load_dword v56, v86, s[78:79]
	s_nop 9
	v_add_f32_e32 v44, v44, v112
	v_add_f32_e32 v45, v45, v113
	v_add_f32_e32 v46, v46, v114
	v_add_f32_e32 v47, v47, v115
	v_mul_f32_e32 v44, v44, v116
	v_mul_f32_e32 v45, v45, v117
	v_mul_f32_e32 v46, v46, v118
	v_mul_f32_e32 v47, v47, v119
	v_cvt_pk_bf16_f32 v40, v44, v45
	v_cvt_pk_bf16_f32 v41, v46, v47
	global_store_short v81, v40, s[66:67]
	global_store_short_d16_hi v82, v40, s[66:67]
	global_store_short v83, v41, s[66:67]
	global_store_short_d16_hi v84, v41, s[66:67]

.Lssd1_loop:
.Lssd1_blk0:
	s_nop 15
	s_add_i32 s0, s76, -1
	s_add_i32 s78, s57, 1
	s_min_i32 s78, s78, s0
	s_add_i32 s79, s57, 2
	s_min_i32 s79, s79, s0
	s_add_i32 s80, s57, 3
	s_min_i32 s80, s80, s0
	s_lshl_b32 s0, s79, 9
	s_add_u32 s72, s58, s0
	s_addc_u32 s73, s59, 0
	s_mul_i32 s0, s57, 0x2a000
	s_add_u32 s62, s28, s0
	s_addc_u32 s63, s29, 0
	s_mul_i32 s0, s78, 0x2a000
	s_add_u32 s64, s28, s0
	s_addc_u32 s65, s29, 0
	s_add_u32 s68, s30, s0
	s_addc_u32 s69, s31, 0
	s_mul_i32 s0, s79, 0x2a000
	s_add_u32 s66, s28, s0
	s_addc_u32 s67, s29, 0
	s_add_u32 s70, s30, s0
	s_addc_u32 s71, s31, 0
	s_mul_i32 s0, s80, 0x2a000
	s_add_u32 s74, s60, s0
	s_addc_u32 s75, s61, 0
	s_waitcnt vmcnt(37)
	v_add_f32_e32 v40, s14, v60
	v_mul_f32_e32 v41, 0x3fb8aa3b, v40
	v_exp_f32_e32 v41, v41
	s_nop 0
	v_add_f32_e32 v41, 1.0, v41
	v_log_f32_e32 v41, v41
	s_nop 0
	v_mul_f32_e32 v41, 0x3f317218, v41
	v_cmp_lt_f32_e32 vcc, 0x41a00000, v40
	s_nop 1
	v_cndmask_b32_e32 v122, v41, v40, vcc
	v_mul_f32_e32 v40, s25, v122
	s_nop 1
	v_add_f32_dpp v41, v40, v40 row_shr:1 row_mask:0xf bank_mask:0xf bound_ctrl:1
	s_nop 1
	v_add_f32_dpp v40, v41, v41 row_shr:2 row_mask:0xf bank_mask:0xf bound_ctrl:1
	s_nop 1
	v_add_f32_dpp v41, v40, v40 row_shr:4 row_mask:0xf bank_mask:0xf bound_ctrl:1
	s_nop 1
	v_add_f32_dpp v121, v41, v41 row_shr:8 row_mask:0xf bank_mask:0xf bound_ctrl:1
	s_nop 0
	v_readlane_b32 s32, v121, 15
	ds_bpermute_b32 v96, v88, v121
	ds_bpermute_b32 v97, v89, v121
	ds_bpermute_b32 v98, v90, v121
	ds_bpermute_b32 v99, v91, v121
	ds_bpermute_b32 v104, v88, v122
	ds_bpermute_b32 v105, v89, v122
	ds_bpermute_b32 v106, v90, v122
	ds_bpermute_b32 v107, v91, v122
	v_exp_f32_e32 v120, s32
	s_waitcnt lgkmcnt(0)
	v_sub_f32_e32 v108, s32, v96
	v_mul_f32_e32 v104, v48, v104
	v_sub_f32_e32 v109, s32, v97
	v_mul_f32_e32 v105, v49, v105
	v_sub_f32_e32 v110, s32, v98
	v_mul_f32_e32 v106, v50, v106
	v_sub_f32_e32 v111, s32, v99
	v_mul_f32_e32 v107, v51, v107
	v_exp_f32_e32 v108, v108
	v_exp_f32_e32 v109, v109
	v_exp_f32_e32 v110, v110
	v_exp_f32_e32 v111, v111
	v_mul_f32_e32 v108, v104, v108
	v_mul_f32_e32 v109, v105, v109
	v_mul_f32_e32 v110, v106, v110
	v_mul_f32_e32 v111, v107, v111
	s_waitcnt vmcnt(56)
	v_mfma_f32_16x16x4_f32 v[36:39], v4, v20, 0
	v_mfma_f32_16x16x4_f32 v[44:47], v20, v72, 0
	global_load_short_d16_hi v20, v80, s[70:71] offset:512
	global_load_short_d16_hi v4, v80, s[70:71] offset:0
	s_waitcnt vmcnt(56)
	v_mfma_f32_16x16x4_f32 v[36:39], v5, v21, v[36:39]
	v_mfma_f32_16x16x4_f32 v[44:47], v21, v73, v[44:47]
	global_load_short_d16_hi v21, v80, s[70:71] offset:514
	global_load_short_d16_hi v5, v80, s[70:71] offset:2
	s_waitcnt vmcnt(56)
	v_mfma_f32_16x16x4_f32 v[36:39], v6, v22, v[36:39]
	v_mfma_f32_16x16x4_f32 v[44:47], v22, v74, v[44:47]
	global_load_short_d16_hi v22, v80, s[70:71] offset:516
	global_load_short_d16_hi v6, v80, s[70:71] offset:4
	s_waitcnt vmcnt(56)
	v_mfma_f32_16x16x4_f32 v[36:39], v7, v23, v[36:39]
	v_mfma_f32_16x16x4_f32 v[44:47], v23, v75, v[44:47]
	global_load_short_d16_hi v23, v80, s[70:71] offset:518
	global_load_short_d16_hi v7, v80, s[70:71] offset:6
	s_waitcnt vmcnt(56)
	v_mfma_f32_16x16x4_f32 v[36:39], v8, v24, v[36:39]
	v_mfma_f32_16x16x4_f32 v[44:47], v24, v76, v[44:47]
	global_load_short_d16_hi v24, v80, s[70:71] offset:544
	global_load_short_d16_hi v8, v80, s[70:71] offset:32
	s_waitcnt vmcnt(56)
	v_mfma_f32_16x16x4_f32 v[36:39], v9, v25, v[36:39]
	v_mfma_f32_16x16x4_f32 v[44:47], v25, v77, v[44:47]
	global_load_short_d16_hi v25, v80, s[70:71] offset:546
	global_load_short_d16_hi v9, v80, s[70:71] offset:34
	s_waitcnt vmcnt(56)
	v_mfma_f32_16x16x4_f32 v[36:39], v10, v26, v[36:39]
	v_mfma_f32_16x16x4_f32 v[44:47], v26, v78, v[44:47]
	global_load_short_d16_hi v26, v80, s[70:71] offset:548
	global_load_short_d16_hi v10, v80, s[70:71] offset:36
	s_waitcnt vmcnt(56)
	v_mfma_f32_16x16x4_f32 v[36:39], v11, v27, v[36:39]
	v_mfma_f32_16x16x4_f32 v[44:47], v27, v79, v[44:47]
	global_load_short_d16_hi v27, v80, s[70:71] offset:550
	global_load_short_d16_hi v11, v80, s[70:71] offset:38
	s_cmp_eq_u32 s77, 0
	s_cbranch_scc1 .Lssd1_w0_0
	s_nop 5
	ds_write_b128 v123, v[36:39] offset:0
	ds_write_b128 v123, v[44:47] offset:4096
	s_cmp_eq_u32 s77, 1
	s_cbranch_scc0 .Lssd1_nw1_0
	s_waitcnt vmcnt(29)
	v_mul_f32_e32 v116, 0xbfb8aa3b, v56
	v_mul_f32_e32 v117, 0xbfb8aa3b, v57
	v_mul_f32_e32 v118, 0xbfb8aa3b, v58
	v_mul_f32_e32 v119, 0xbfb8aa3b, v59
	v_exp_f32_e32 v116, v116
	v_exp_f32_e32 v117, v117
	v_exp_f32_e32 v118, v118
	v_exp_f32_e32 v119, v119
	v_add_f32_e32 v116, 1.0, v116
	v_add_f32_e32 v117, 1.0, v117
	v_add_f32_e32 v118, 1.0, v118
	v_add_f32_e32 v119, 1.0, v119
	v_rcp_f32_e32 v116, v116
	v_rcp_f32_e32 v117, v117
	v_rcp_f32_e32 v118, v118
	v_rcp_f32_e32 v119, v119
	v_mul_f32_e32 v116, v116, v56
	v_mul_f32_e32 v117, v117, v57
	v_mul_f32_e32 v118, v118, v58
	v_mul_f32_e32 v119, v119, v59
	ds_write_b128 v124, v[116:119] offset:16384
	global_load_short_d16_hi v56, v81, s[64:65]
	global_load_short_d16_hi v57, v82, s[64:65]
	global_load_short_d16_hi v58, v83, s[64:65]
	global_load_short_d16_hi v59, v84, s[64:65]
	s_branch .Lssd1_pub_0
.Lssd1_nw1_0:
	s_cmp_eq_u32 s77, 2
	s_cbranch_scc0 .Lssd1_pub_0
	v_sub_f32_e32 v100, v121, v96
	v_sub_f32_e32 v101, v121, v97
	v_sub_f32_e32 v102, v121, v98
	v_sub_f32_e32 v103, v121, v99
	v_min_f32_e32 v100, 0, v100
	v_min_f32_e32 v101, 0, v101
	v_min_f32_e32 v102, 0, v102
	v_min_f32_e32 v103, 0, v103
	v_add_f32_e32 v100, v92, v100
	v_add_f32_e32 v101, v93, v101
	v_add_f32_e32 v102, v94, v102
	v_add_f32_e32 v103, v95, v103
	v_exp_f32_e32 v100, v100
	v_exp_f32_e32 v101, v101
	v_exp_f32_e32 v102, v102
	v_exp_f32_e32 v103, v103
	v_exp_f32_e32 v96, v96
	v_exp_f32_e32 v97, v97
	v_exp_f32_e32 v98, v98
	v_exp_f32_e32 v99, v99
	ds_write_b128 v124, v[100:103] offset:17408
	ds_write_b128 v124, v[96:99] offset:18432

.Lssd1_w0_0:
	s_barrier
	ds_read_b128 v[128:131], v124 offset:1024
	ds_read_b128 v[132:135], v124 offset:5120
	ds_read_b128 v[136:139], v124 offset:2048
	ds_read_b128 v[140:143], v124 offset:6144
	ds_read_b128 v[144:147], v124 offset:3072
	ds_read_b128 v[150:153], v124 offset:7168
	ds_read_b128 v[116:119], v124 offset:16384
	ds_read_b128 v[100:103], v124 offset:17408
	ds_read_b128 v[96:99], v124 offset:18432
	v_mul_f32_e32 v112, s27, v48
	v_mul_f32_e32 v113, s27, v49
	v_mul_f32_e32 v114, s27, v50
	v_mul_f32_e32 v115, s27, v51
	s_waitcnt lgkmcnt(0)
	v_add_f32_e32 v36, v36, v128
	v_add_f32_e32 v37, v37, v129
	v_add_f32_e32 v38, v38, v130
	v_add_f32_e32 v39, v39, v131
	v_add_f32_e32 v44, v44, v132
	v_add_f32_e32 v45, v45, v133
	v_add_f32_e32 v46, v46, v134
	v_add_f32_e32 v47, v47, v135
	v_add_f32_e32 v36, v36, v136
	v_add_f32_e32 v37, v37, v137
	v_add_f32_e32 v38, v38, v138
	v_add_f32_e32 v39, v39, v139
	v_add_f32_e32 v44, v44, v140
	v_add_f32_e32 v45, v45, v141
	v_add_f32_e32 v46, v46, v142
	v_add_f32_e32 v47, v47, v143
	v_add_f32_e32 v36, v36, v144
	v_add_f32_e32 v37, v37, v145
	v_add_f32_e32 v38, v38, v146
	v_add_f32_e32 v39, v39, v147
	v_add_f32_e32 v44, v44, v150
	v_add_f32_e32 v45, v45, v151
	v_add_f32_e32 v46, v46, v152
	v_add_f32_e32 v47, v47, v153
	v_mul_f32_e32 v36, v36, v100
	v_mul_f32_e32 v37, v37, v101
	v_mul_f32_e32 v38, v38, v102
	v_mul_f32_e32 v39, v39, v103
	v_mul_f32_e32 v44, v44, v96
	v_mul_f32_e32 v45, v45, v97
	v_mul_f32_e32 v46, v46, v98
	v_mul_f32_e32 v47, v47, v99
	s_nop 0
	s_nop 0
	v_mfma_f32_16x16x4_f32 v[44:47], v36, v104, v[44:47]
	v_mfma_f32_16x16x4_f32 v[44:47], v37, v105, v[44:47]
	v_mfma_f32_16x16x4_f32 v[44:47], v38, v106, v[44:47]
	v_mfma_f32_16x16x4_f32 v[44:47], v39, v107, v[44:47]
	global_load_dword v56, v86, s[74:75]
	s_nop 9
	v_add_f32_e32 v44, v44, v112
	v_add_f32_e32 v45, v45, v113
	v_add_f32_e32 v46, v46, v114
	v_add_f32_e32 v47, v47, v115
	v_mul_f32_e32 v44, v44, v116
	v_mul_f32_e32 v45, v45, v117
	v_mul_f32_e32 v46, v46, v118
	v_mul_f32_e32 v47, v47, v119
	v_cvt_pk_bf16_f32 v40, v44, v45
	v_cvt_pk_bf16_f32 v41, v46, v47
	global_store_short v81, v40, s[62:63]
	global_store_short_d16_hi v82, v40, s[62:63]
	global_store_short v83, v41, s[62:63]
	global_store_short_d16_hi v84, v41, s[62:63]

.Lssd1_blk1:
	s_nop 15
	s_add_i32 s0, s76, -1
	s_add_i32 s78, s57, 1
	s_min_i32 s78, s78, s0
	s_add_i32 s79, s57, 2
	s_min_i32 s79, s79, s0
	s_add_i32 s80, s57, 3
	s_min_i32 s80, s80, s0
	s_lshl_b32 s0, s79, 9
	s_add_u32 s72, s58, s0
	s_addc_u32 s73, s59, 0
	s_mul_i32 s0, s57, 0x2a000
	s_add_u32 s62, s28, s0
	s_addc_u32 s63, s29, 0
	s_mul_i32 s0, s78, 0x2a000
	s_add_u32 s64, s28, s0
	s_addc_u32 s65, s29, 0
	s_add_u32 s68, s30, s0
	s_addc_u32 s69, s31, 0
	s_mul_i32 s0, s79, 0x2a000
	s_add_u32 s66, s28, s0
	s_addc_u32 s67, s29, 0
	s_add_u32 s70, s30, s0
	s_addc_u32 s71, s31, 0
	s_mul_i32 s0, s80, 0x2a000
	s_add_u32 s74, s60, s0
	s_addc_u32 s75, s61, 0
	s_waitcnt vmcnt(37)
	v_add_f32_e32 v40, s14, v61
	v_mul_f32_e32 v41, 0x3fb8aa3b, v40
	v_exp_f32_e32 v41, v41
	s_nop 0
	v_add_f32_e32 v41, 1.0, v41
	v_log_f32_e32 v41, v41
	s_nop 0
	v_mul_f32_e32 v41, 0x3f317218, v41
	v_cmp_lt_f32_e32 vcc, 0x41a00000, v40
	s_nop 1
	v_cndmask_b32_e32 v122, v41, v40, vcc
	v_mul_f32_e32 v40, s25, v122
	s_nop 1
	v_add_f32_dpp v41, v40, v40 row_shr:1 row_mask:0xf bank_mask:0xf bound_ctrl:1
	s_nop 1
	v_add_f32_dpp v40, v41, v41 row_shr:2 row_mask:0xf bank_mask:0xf bound_ctrl:1
	s_nop 1
	v_add_f32_dpp v41, v40, v40 row_shr:4 row_mask:0xf bank_mask:0xf bound_ctrl:1
	s_nop 1
	v_add_f32_dpp v121, v41, v41 row_shr:8 row_mask:0xf bank_mask:0xf bound_ctrl:1
	s_nop 0
	v_readlane_b32 s32, v121, 15
	ds_bpermute_b32 v96, v88, v121
	ds_bpermute_b32 v97, v89, v121
	ds_bpermute_b32 v98, v90, v121
	ds_bpermute_b32 v99, v91, v121
	ds_bpermute_b32 v104, v88, v122
	ds_bpermute_b32 v105, v89, v122
	ds_bpermute_b32 v106, v90, v122
	ds_bpermute_b32 v107, v91, v122
	v_exp_f32_e32 v120, s32
	s_waitcnt lgkmcnt(0)
	v_sub_f32_e32 v108, s32, v96
	v_mul_f32_e32 v104, v52, v104
	v_sub_f32_e32 v109, s32, v97
	v_mul_f32_e32 v105, v53, v105
	v_sub_f32_e32 v110, s32, v98
	v_mul_f32_e32 v106, v54, v106
	v_sub_f32_e32 v111, s32, v99
	v_mul_f32_e32 v107, v55, v107
	v_exp_f32_e32 v108, v108
	v_exp_f32_e32 v109, v109
	v_exp_f32_e32 v110, v110
	v_exp_f32_e32 v111, v111
	v_mul_f32_e32 v108, v104, v108
	v_mul_f32_e32 v109, v105, v109
	v_mul_f32_e32 v110, v106, v110
	v_mul_f32_e32 v111, v107, v111
	s_waitcnt vmcnt(56)
	v_mfma_f32_16x16x4_f32 v[36:39], v12, v28, 0
	v_mfma_f32_16x16x4_f32 v[44:47], v28, v72, 0
	global_load_short_d16_hi v28, v80, s[70:71] offset:512
	global_load_short_d16_hi v12, v80, s[70:71] offset:0
	s_waitcnt vmcnt(56)
	v_mfma_f32_16x16x4_f32 v[36:39], v13, v29, v[36:39]
	v_mfma_f32_16x16x4_f32 v[44:47], v29, v73, v[44:47]
	global_load_short_d16_hi v29, v80, s[70:71] offset:514
	global_load_short_d16_hi v13, v80, s[70:71] offset:2
	s_waitcnt vmcnt(56)
	v_mfma_f32_16x16x4_f32 v[36:39], v14, v30, v[36:39]
	v_mfma_f32_16x16x4_f32 v[44:47], v30, v74, v[44:47]
	global_load_short_d16_hi v30, v80, s[70:71] offset:516
	global_load_short_d16_hi v14, v80, s[70:71] offset:4
	s_waitcnt vmcnt(56)
	v_mfma_f32_16x16x4_f32 v[36:39], v15, v31, v[36:39]
	v_mfma_f32_16x16x4_f32 v[44:47], v31, v75, v[44:47]
	global_load_short_d16_hi v31, v80, s[70:71] offset:518
	global_load_short_d16_hi v15, v80, s[70:71] offset:6
	s_waitcnt vmcnt(56)
	v_mfma_f32_16x16x4_f32 v[36:39], v16, v32, v[36:39]
	v_mfma_f32_16x16x4_f32 v[44:47], v32, v76, v[44:47]
	global_load_short_d16_hi v32, v80, s[70:71] offset:544
	global_load_short_d16_hi v16, v80, s[70:71] offset:32
	s_waitcnt vmcnt(56)
	v_mfma_f32_16x16x4_f32 v[36:39], v17, v33, v[36:39]
	v_mfma_f32_16x16x4_f32 v[44:47], v33, v77, v[44:47]
	global_load_short_d16_hi v33, v80, s[70:71] offset:546
	global_load_short_d16_hi v17, v80, s[70:71] offset:34
	s_waitcnt vmcnt(56)
	v_mfma_f32_16x16x4_f32 v[36:39], v18, v34, v[36:39]
	v_mfma_f32_16x16x4_f32 v[44:47], v34, v78, v[44:47]
	global_load_short_d16_hi v34, v80, s[70:71] offset:548
	global_load_short_d16_hi v18, v80, s[70:71] offset:36
	s_waitcnt vmcnt(56)
	v_mfma_f32_16x16x4_f32 v[36:39], v19, v35, v[36:39]
	v_mfma_f32_16x16x4_f32 v[44:47], v35, v79, v[44:47]
	global_load_short_d16_hi v35, v80, s[70:71] offset:550
	global_load_short_d16_hi v19, v80, s[70:71] offset:38
	s_cmp_eq_u32 s77, 0
	s_cbranch_scc1 .Lssd1_w0_1
	s_nop 5
	ds_write_b128 v123, v[36:39] offset:8192
	ds_write_b128 v123, v[44:47] offset:12288
	s_cmp_eq_u32 s77, 1
	s_cbranch_scc0 .Lssd1_nw1_1
	s_waitcnt vmcnt(29)
	v_mul_f32_e32 v116, 0xbfb8aa3b, v56
	v_mul_f32_e32 v117, 0xbfb8aa3b, v57
	v_mul_f32_e32 v118, 0xbfb8aa3b, v58
	v_mul_f32_e32 v119, 0xbfb8aa3b, v59
	v_exp_f32_e32 v116, v116
	v_exp_f32_e32 v117, v117
	v_exp_f32_e32 v118, v118
	v_exp_f32_e32 v119, v119
	v_add_f32_e32 v116, 1.0, v116
	v_add_f32_e32 v117, 1.0, v117
	v_add_f32_e32 v118, 1.0, v118
	v_add_f32_e32 v119, 1.0, v119
	v_rcp_f32_e32 v116, v116
	v_rcp_f32_e32 v117, v117
	v_rcp_f32_e32 v118, v118
	v_rcp_f32_e32 v119, v119
	v_mul_f32_e32 v116, v116, v56
	v_mul_f32_e32 v117, v117, v57
	v_mul_f32_e32 v118, v118, v58
	v_mul_f32_e32 v119, v119, v59
	ds_write_b128 v124, v[116:119] offset:20480
	global_load_short_d16_hi v56, v81, s[64:65]
	global_load_short_d16_hi v57, v82, s[64:65]
	global_load_short_d16_hi v58, v83, s[64:65]
	global_load_short_d16_hi v59, v84, s[64:65]
	s_branch .Lssd1_pub_1
.Lssd1_nw1_1:
	s_cmp_eq_u32 s77, 2
	s_cbranch_scc0 .Lssd1_pub_1
	v_sub_f32_e32 v100, v121, v96
	v_sub_f32_e32 v101, v121, v97
	v_sub_f32_e32 v102, v121, v98
	v_sub_f32_e32 v103, v121, v99
	v_min_f32_e32 v100, 0, v100
	v_min_f32_e32 v101, 0, v101
	v_min_f32_e32 v102, 0, v102
	v_min_f32_e32 v103, 0, v103
	v_add_f32_e32 v100, v92, v100
	v_add_f32_e32 v101, v93, v101
	v_add_f32_e32 v102, v94, v102
	v_add_f32_e32 v103, v95, v103
	v_exp_f32_e32 v100, v100
	v_exp_f32_e32 v101, v101
	v_exp_f32_e32 v102, v102
	v_exp_f32_e32 v103, v103
	v_exp_f32_e32 v96, v96
	v_exp_f32_e32 v97, v97
	v_exp_f32_e32 v98, v98
	v_exp_f32_e32 v99, v99
	ds_write_b128 v124, v[100:103] offset:21504
	ds_write_b128 v124, v[96:99] offset:22528

.Lssd1_w0_1:
	s_barrier
	ds_read_b128 v[128:131], v124 offset:9216
	ds_read_b128 v[132:135], v124 offset:13312
	ds_read_b128 v[136:139], v124 offset:10240
	ds_read_b128 v[140:143], v124 offset:14336
	ds_read_b128 v[144:147], v124 offset:11264
	ds_read_b128 v[150:153], v124 offset:15360
	ds_read_b128 v[116:119], v124 offset:20480
	ds_read_b128 v[100:103], v124 offset:21504
	ds_read_b128 v[96:99], v124 offset:22528
	v_mul_f32_e32 v112, s27, v52
	v_mul_f32_e32 v113, s27, v53
	v_mul_f32_e32 v114, s27, v54
	v_mul_f32_e32 v115, s27, v55
	s_waitcnt lgkmcnt(0)
	v_add_f32_e32 v36, v36, v128
	v_add_f32_e32 v37, v37, v129
	v_add_f32_e32 v38, v38, v130
	v_add_f32_e32 v39, v39, v131
	v_add_f32_e32 v44, v44, v132
	v_add_f32_e32 v45, v45, v133
	v_add_f32_e32 v46, v46, v134
	v_add_f32_e32 v47, v47, v135
	v_add_f32_e32 v36, v36, v136
	v_add_f32_e32 v37, v37, v137
	v_add_f32_e32 v38, v38, v138
	v_add_f32_e32 v39, v39, v139
	v_add_f32_e32 v44, v44, v140
	v_add_f32_e32 v45, v45, v141
	v_add_f32_e32 v46, v46, v142
	v_add_f32_e32 v47, v47, v143
	v_add_f32_e32 v36, v36, v144
	v_add_f32_e32 v37, v37, v145
	v_add_f32_e32 v38, v38, v146
	v_add_f32_e32 v39, v39, v147
	v_add_f32_e32 v44, v44, v150
	v_add_f32_e32 v45, v45, v151
	v_add_f32_e32 v46, v46, v152
	v_add_f32_e32 v47, v47, v153
	v_mul_f32_e32 v36, v36, v100
	v_mul_f32_e32 v37, v37, v101
	v_mul_f32_e32 v38, v38, v102
	v_mul_f32_e32 v39, v39, v103
	v_mul_f32_e32 v44, v44, v96
	v_mul_f32_e32 v45, v45, v97
	v_mul_f32_e32 v46, v46, v98
	v_mul_f32_e32 v47, v47, v99
	s_nop 0
	s_nop 0
	v_mfma_f32_16x16x4_f32 v[44:47], v36, v104, v[44:47]
	v_mfma_f32_16x16x4_f32 v[44:47], v37, v105, v[44:47]
	v_mfma_f32_16x16x4_f32 v[44:47], v38, v106, v[44:47]
	v_mfma_f32_16x16x4_f32 v[44:47], v39, v107, v[44:47]
	global_load_dword v56, v86, s[74:75]
	s_nop 9
	v_add_f32_e32 v44, v44, v112
	v_add_f32_e32 v45, v45, v113
	v_add_f32_e32 v46, v46, v114
	v_add_f32_e32 v47, v47, v115
	v_mul_f32_e32 v44, v44, v116
	v_mul_f32_e32 v45, v45, v117
	v_mul_f32_e32 v46, v46, v118
	v_mul_f32_e32 v47, v47, v119
	v_cvt_pk_bf16_f32 v40, v44, v45
	v_cvt_pk_bf16_f32 v41, v46, v47
	global_store_short v81, v40, s[62:63]
	global_store_short_d16_hi v82, v40, s[62:63]
	global_store_short v83, v41, s[62:63]
	global_store_short_d16_hi v84, v41, s[62:63]
